# W1 SiLU epilogue rewritten by hand: packed -log2e scale (constant in SGPR pair) and packed +1, batched exp/rcp per 8 outputs, store addresses hoisted; bit-identical results
# speedup vs baseline: 1.0215x; 1.0083x over previous
; DI unsigned pk2(float lo, float hi) { f32x2 v = {lo, hi}; bf16x2v b = __builtin_convertvector(v, bf16x2v); return __builtin_bit_cast(unsigned, b); }
; DI float siluf_(float x) { return x * __builtin_amdgcn_rcpf(1.f + __builtin_amdgcn_exp2f(-LOG2E * x)); }
;   DI void operator()(int tok0, int feat0, f32x16 (&acc)[2][2], int r, int hh) const {
;     const int u0 = (feat0 >> 6) * 32;
; #pragma unroll
;     for (int mt = 0; mt < 2; ++mt) {
;       bf16_t* dst = act + (size_t)(tok0 + mt * 32 + r) * DFF + u0 + 16 * hh;
; #pragma unroll
;       for (int gp = 0; gp < 2; ++gp) {
;         u32x4 o;
; #pragma unroll
;         for (int q = 0; q < 4; ++q) { const int i = 8 * gp + 2 * q; o[q] = pk2(siluf_(acc[0][mt][i]) * acc[1][mt][i], siluf_(acc[0][mt][i + 1]) * acc[1][mt][i + 1]); }
;         *(u32x4*)(dst + 8 * gp) = o;
;       }
;     }
;   }
.Lkexit_4:
	v_mov_b32_e32 v0, v192
	v_mov_b64_e32 v[166:167], s[6:7]
	v_ashrrev_i32_e32 v164, 1, v0
	v_and_b32_e32 v164, 0xffffff80, v164
	v_add_u32_e32 v164, s3, v164
	v_ashrrev_i32_e32 v164, 1, v164
	v_and_b32_e32 v165, 0xdf, v0
	v_or_b32_e32 v187, s8, v165
	v_ashrrev_i32_e32 v165, 31, v164
	v_mad_i64_i32 v[188:189], s[12:13], v187, s69, v[166:167]
	v_lshlrev_b64 v[168:169], 1, v[164:165]
	v_lshl_add_u64 v[164:165], v[188:189], 0, v[168:169]
	v_and_b32_e32 v0, 32, v0
	v_lshl_add_u64 v[164:165], v[164:165], 0, v[0:1]
	v_or_b32_e32 v188, 32, v187
	v_mad_i64_i32 v[188:189], s[12:13], v188, s69, v[166:167]
	v_lshl_add_u64 v[188:189], v[188:189], 0, v[168:169]
	v_lshl_add_u64 v[188:189], v[188:189], 0, v[0:1]
	s_mov_b32 s100, 0xbfb8aa3b
	v_pk_mul_f32 v[238:239], v[114:115], s[100:101] op_sel_hi:[1,0]
	v_pk_mul_f32 v[240:241], v[116:117], s[100:101] op_sel_hi:[1,0]
	v_pk_mul_f32 v[242:243], v[118:119], s[100:101] op_sel_hi:[1,0]
	v_pk_mul_f32 v[244:245], v[120:121], s[100:101] op_sel_hi:[1,0]
	v_exp_f32_e32 v238, v238
	v_exp_f32_e32 v239, v239
	v_exp_f32_e32 v240, v240
	v_exp_f32_e32 v241, v241
	v_exp_f32_e32 v242, v242
	v_exp_f32_e32 v243, v243
	v_exp_f32_e32 v244, v244
	v_exp_f32_e32 v245, v245
	v_pk_add_f32 v[238:239], v[238:239], 1.0 op_sel_hi:[1,0]
	v_pk_add_f32 v[240:241], v[240:241], 1.0 op_sel_hi:[1,0]
	v_pk_add_f32 v[242:243], v[242:243], 1.0 op_sel_hi:[1,0]
	v_pk_add_f32 v[244:245], v[244:245], 1.0 op_sel_hi:[1,0]
	v_rcp_f32_e32 v238, v238
	v_rcp_f32_e32 v239, v239
	v_rcp_f32_e32 v240, v240
	v_rcp_f32_e32 v241, v241
	v_rcp_f32_e32 v242, v242
	v_rcp_f32_e32 v243, v243
	v_rcp_f32_e32 v244, v244
	v_rcp_f32_e32 v245, v245
	v_pk_mul_f32 v[238:239], v[114:115], v[238:239]
	v_pk_mul_f32 v[240:241], v[116:117], v[240:241]
	v_pk_mul_f32 v[242:243], v[118:119], v[242:243]
	v_pk_mul_f32 v[244:245], v[120:121], v[244:245]
	v_pk_mul_f32 v[238:239], v[98:99], v[238:239]
	v_pk_mul_f32 v[240:241], v[100:101], v[240:241]
	v_pk_mul_f32 v[242:243], v[102:103], v[242:243]
	v_pk_mul_f32 v[244:245], v[104:105], v[244:245]
	v_cvt_pk_bf16_f32 v238, v238, v239
	v_cvt_pk_bf16_f32 v239, v240, v241
	v_cvt_pk_bf16_f32 v240, v242, v243
	v_cvt_pk_bf16_f32 v241, v244, v245
	global_store_dwordx4 v[164:165], v[238:241], off
	s_nop 1
	v_pk_mul_f32 v[238:239], v[122:123], s[100:101] op_sel_hi:[1,0]
	v_pk_mul_f32 v[240:241], v[124:125], s[100:101] op_sel_hi:[1,0]
	v_pk_mul_f32 v[242:243], v[126:127], s[100:101] op_sel_hi:[1,0]
	v_pk_mul_f32 v[244:245], v[128:129], s[100:101] op_sel_hi:[1,0]
	v_exp_f32_e32 v238, v238
	v_exp_f32_e32 v239, v239
	v_exp_f32_e32 v240, v240
	v_exp_f32_e32 v241, v241
	v_exp_f32_e32 v242, v242
	v_exp_f32_e32 v243, v243
	v_exp_f32_e32 v244, v244
	v_exp_f32_e32 v245, v245
	v_pk_add_f32 v[238:239], v[238:239], 1.0 op_sel_hi:[1,0]
	v_pk_add_f32 v[240:241], v[240:241], 1.0 op_sel_hi:[1,0]
	v_pk_add_f32 v[242:243], v[242:243], 1.0 op_sel_hi:[1,0]
	v_pk_add_f32 v[244:245], v[244:245], 1.0 op_sel_hi:[1,0]
	v_rcp_f32_e32 v238, v238
	v_rcp_f32_e32 v239, v239
	v_rcp_f32_e32 v240, v240
	v_rcp_f32_e32 v241, v241
	v_rcp_f32_e32 v242, v242
	v_rcp_f32_e32 v243, v243
	v_rcp_f32_e32 v244, v244
	v_rcp_f32_e32 v245, v245
	v_pk_mul_f32 v[238:239], v[122:123], v[238:239]
	v_pk_mul_f32 v[240:241], v[124:125], v[240:241]
	v_pk_mul_f32 v[242:243], v[126:127], v[242:243]
	v_pk_mul_f32 v[244:245], v[128:129], v[244:245]
	v_pk_mul_f32 v[238:239], v[106:107], v[238:239]
	v_pk_mul_f32 v[240:241], v[108:109], v[240:241]
	v_pk_mul_f32 v[242:243], v[110:111], v[242:243]
	v_pk_mul_f32 v[244:245], v[112:113], v[244:245]
	v_cvt_pk_bf16_f32 v238, v238, v239
	v_cvt_pk_bf16_f32 v239, v240, v241
	v_cvt_pk_bf16_f32 v240, v242, v243
	v_cvt_pk_bf16_f32 v241, v244, v245
	global_store_dwordx4 v[164:165], v[238:241], off offset:16
	s_nop 1
	v_pk_mul_f32 v[238:239], v[82:83], s[100:101] op_sel_hi:[1,0]
	v_pk_mul_f32 v[240:241], v[84:85], s[100:101] op_sel_hi:[1,0]
	v_pk_mul_f32 v[242:243], v[86:87], s[100:101] op_sel_hi:[1,0]
	v_pk_mul_f32 v[244:245], v[88:89], s[100:101] op_sel_hi:[1,0]
	v_exp_f32_e32 v238, v238
	v_exp_f32_e32 v239, v239
	v_exp_f32_e32 v240, v240
	v_exp_f32_e32 v241, v241
	v_exp_f32_e32 v242, v242
	v_exp_f32_e32 v243, v243
	v_exp_f32_e32 v244, v244
	v_exp_f32_e32 v245, v245
	v_pk_add_f32 v[238:239], v[238:239], 1.0 op_sel_hi:[1,0]
	v_pk_add_f32 v[240:241], v[240:241], 1.0 op_sel_hi:[1,0]
	v_pk_add_f32 v[242:243], v[242:243], 1.0 op_sel_hi:[1,0]
	v_pk_add_f32 v[244:245], v[244:245], 1.0 op_sel_hi:[1,0]
	v_rcp_f32_e32 v238, v238
	v_rcp_f32_e32 v239, v239
	v_rcp_f32_e32 v240, v240
	v_rcp_f32_e32 v241, v241
	v_rcp_f32_e32 v242, v242
	v_rcp_f32_e32 v243, v243
	v_rcp_f32_e32 v244, v244
	v_rcp_f32_e32 v245, v245
	v_pk_mul_f32 v[238:239], v[82:83], v[238:239]
	v_pk_mul_f32 v[240:241], v[84:85], v[240:241]
	v_pk_mul_f32 v[242:243], v[86:87], v[242:243]
	v_pk_mul_f32 v[244:245], v[88:89], v[244:245]
	v_pk_mul_f32 v[238:239], v[66:67], v[238:239]
	v_pk_mul_f32 v[240:241], v[68:69], v[240:241]
	v_pk_mul_f32 v[242:243], v[70:71], v[242:243]
	v_pk_mul_f32 v[244:245], v[72:73], v[244:245]
	v_cvt_pk_bf16_f32 v238, v238, v239
	v_cvt_pk_bf16_f32 v239, v240, v241
	v_cvt_pk_bf16_f32 v240, v242, v243
	v_cvt_pk_bf16_f32 v241, v244, v245
	global_store_dwordx4 v[188:189], v[238:241], off
	s_nop 1
	v_pk_mul_f32 v[238:239], v[90:91], s[100:101] op_sel_hi:[1,0]
	v_pk_mul_f32 v[240:241], v[92:93], s[100:101] op_sel_hi:[1,0]
	v_pk_mul_f32 v[242:243], v[94:95], s[100:101] op_sel_hi:[1,0]
	v_pk_mul_f32 v[244:245], v[96:97], s[100:101] op_sel_hi:[1,0]
	v_exp_f32_e32 v238, v238
	v_exp_f32_e32 v239, v239
	v_exp_f32_e32 v240, v240
	v_exp_f32_e32 v241, v241
	v_exp_f32_e32 v242, v242
	v_exp_f32_e32 v243, v243
; DI unsigned pk2(float lo, float hi) { f32x2 v = {lo, hi}; bf16x2v b = __builtin_convertvector(v, bf16x2v); return __builtin_bit_cast(unsigned, b); }
; DI float siluf_(float x) { return x * __builtin_amdgcn_rcpf(1.f + __builtin_amdgcn_exp2f(-LOG2E * x)); }
;   DI void operator()(int tok0, int feat0, f32x16 (&acc)[2][2], int r, int hh) const {
;     const int u0 = (feat0 >> 6) * 32;
; #pragma unroll
;     for (int mt = 0; mt < 2; ++mt) {
;       bf16_t* dst = act + (size_t)(tok0 + mt * 32 + r) * DFF + u0 + 16 * hh;
; #pragma unroll
;       for (int gp = 0; gp < 2; ++gp) {
;         u32x4 o;
; #pragma unroll
;         for (int q = 0; q < 4; ++q) { const int i = 8 * gp + 2 * q; o[q] = pk2(siluf_(acc[0][mt][i]) * acc[1][mt][i], siluf_(acc[0][mt][i + 1]) * acc[1][mt][i + 1]); }
;         *(u32x4*)(dst + 8 * gp) = o;
;       }
;     }
;   }
	v_exp_f32_e32 v244, v244
	v_exp_f32_e32 v245, v245
	v_pk_add_f32 v[238:239], v[238:239], 1.0 op_sel_hi:[1,0]
	v_pk_add_f32 v[240:241], v[240:241], 1.0 op_sel_hi:[1,0]
	v_pk_add_f32 v[242:243], v[242:243], 1.0 op_sel_hi:[1,0]
	v_pk_add_f32 v[244:245], v[244:245], 1.0 op_sel_hi:[1,0]
	v_rcp_f32_e32 v238, v238
	v_rcp_f32_e32 v239, v239
	v_rcp_f32_e32 v240, v240
	v_rcp_f32_e32 v241, v241
	v_rcp_f32_e32 v242, v242
	v_rcp_f32_e32 v243, v243
	v_rcp_f32_e32 v244, v244
	v_rcp_f32_e32 v245, v245
	v_pk_mul_f32 v[238:239], v[90:91], v[238:239]
	v_pk_mul_f32 v[240:241], v[92:93], v[240:241]
	v_pk_mul_f32 v[242:243], v[94:95], v[242:243]
	v_pk_mul_f32 v[244:245], v[96:97], v[244:245]
	v_pk_mul_f32 v[238:239], v[74:75], v[238:239]
	v_pk_mul_f32 v[240:241], v[76:77], v[240:241]
	v_pk_mul_f32 v[242:243], v[78:79], v[242:243]
	v_pk_mul_f32 v[244:245], v[80:81], v[244:245]
	v_cvt_pk_bf16_f32 v238, v238, v239
	v_cvt_pk_bf16_f32 v239, v240, v241
	v_cvt_pk_bf16_f32 v240, v242, v243
	v_cvt_pk_bf16_f32 v241, v244, v245
	global_store_dwordx4 v[188:189], v[238:241], off offset:16
	s_nop 1
	v_pk_mul_f32 v[238:239], v[50:51], s[100:101] op_sel_hi:[1,0]
	v_pk_mul_f32 v[240:241], v[52:53], s[100:101] op_sel_hi:[1,0]
	v_pk_mul_f32 v[242:243], v[54:55], s[100:101] op_sel_hi:[1,0]
	v_pk_mul_f32 v[244:245], v[56:57], s[100:101] op_sel_hi:[1,0]
	v_exp_f32_e32 v238, v238
	v_exp_f32_e32 v239, v239
	v_exp_f32_e32 v240, v240
	v_exp_f32_e32 v241, v241
	v_exp_f32_e32 v242, v242
	v_exp_f32_e32 v243, v243
	v_exp_f32_e32 v244, v244
	v_exp_f32_e32 v245, v245
	v_pk_add_f32 v[238:239], v[238:239], 1.0 op_sel_hi:[1,0]
	v_pk_add_f32 v[240:241], v[240:241], 1.0 op_sel_hi:[1,0]
	v_pk_add_f32 v[242:243], v[242:243], 1.0 op_sel_hi:[1,0]
	v_pk_add_f32 v[244:245], v[244:245], 1.0 op_sel_hi:[1,0]
	v_rcp_f32_e32 v238, v238
	v_rcp_f32_e32 v239, v239
	v_rcp_f32_e32 v240, v240
	v_rcp_f32_e32 v241, v241
	v_rcp_f32_e32 v242, v242
	v_rcp_f32_e32 v243, v243
	v_rcp_f32_e32 v244, v244
	v_rcp_f32_e32 v245, v245
	v_pk_mul_f32 v[238:239], v[50:51], v[238:239]
	v_pk_mul_f32 v[240:241], v[52:53], v[240:241]
	v_pk_mul_f32 v[242:243], v[54:55], v[242:243]
	v_pk_mul_f32 v[244:245], v[56:57], v[244:245]
	v_pk_mul_f32 v[238:239], v[34:35], v[238:239]
	v_pk_mul_f32 v[240:241], v[36:37], v[240:241]
	v_pk_mul_f32 v[242:243], v[38:39], v[242:243]
	v_pk_mul_f32 v[244:245], v[40:41], v[244:245]
	v_cvt_pk_bf16_f32 v238, v238, v239
	v_cvt_pk_bf16_f32 v239, v240, v241
	v_cvt_pk_bf16_f32 v240, v242, v243
	v_cvt_pk_bf16_f32 v241, v244, v245
	global_store_dwordx4 v[164:165], v[238:241], off offset:64
	s_nop 1
	v_pk_mul_f32 v[238:239], v[58:59], s[100:101] op_sel_hi:[1,0]
	v_pk_mul_f32 v[240:241], v[60:61], s[100:101] op_sel_hi:[1,0]
	v_pk_mul_f32 v[242:243], v[62:63], s[100:101] op_sel_hi:[1,0]
	v_pk_mul_f32 v[244:245], v[64:65], s[100:101] op_sel_hi:[1,0]
	v_exp_f32_e32 v238, v238
	v_exp_f32_e32 v239, v239
	v_exp_f32_e32 v240, v240
	v_exp_f32_e32 v241, v241
	v_exp_f32_e32 v242, v242
	v_exp_f32_e32 v243, v243
	v_exp_f32_e32 v244, v244
	v_exp_f32_e32 v245, v245
	v_pk_add_f32 v[238:239], v[238:239], 1.0 op_sel_hi:[1,0]
	v_pk_add_f32 v[240:241], v[240:241], 1.0 op_sel_hi:[1,0]
	v_pk_add_f32 v[242:243], v[242:243], 1.0 op_sel_hi:[1,0]
	v_pk_add_f32 v[244:245], v[244:245], 1.0 op_sel_hi:[1,0]
	v_rcp_f32_e32 v238, v238
	v_rcp_f32_e32 v239, v239
	v_rcp_f32_e32 v240, v240
	v_rcp_f32_e32 v241, v241
	v_rcp_f32_e32 v242, v242
	v_rcp_f32_e32 v243, v243
	v_rcp_f32_e32 v244, v244
	v_rcp_f32_e32 v245, v245
	v_pk_mul_f32 v[238:239], v[58:59], v[238:239]
	v_pk_mul_f32 v[240:241], v[60:61], v[240:241]
	v_pk_mul_f32 v[242:243], v[62:63], v[242:243]
	v_pk_mul_f32 v[244:245], v[64:65], v[244:245]
	v_pk_mul_f32 v[238:239], v[42:43], v[238:239]
	v_pk_mul_f32 v[240:241], v[44:45], v[240:241]
	v_pk_mul_f32 v[242:243], v[46:47], v[242:243]
	v_pk_mul_f32 v[244:245], v[48:49], v[244:245]
	v_cvt_pk_bf16_f32 v238, v238, v239
	v_cvt_pk_bf16_f32 v239, v240, v241
	v_cvt_pk_bf16_f32 v240, v242, v243
	v_cvt_pk_bf16_f32 v241, v244, v245
	global_store_dwordx4 v[164:165], v[238:241], off offset:80
; #define GAS __attribute__((address_space(1)))
; DI unsigned pk2(float lo, float hi) { f32x2 v = {lo, hi}; bf16x2v b = __builtin_convertvector(v, bf16x2v); return __builtin_bit_cast(unsigned, b); }
; DI float siluf_(float x) { return x * __builtin_amdgcn_rcpf(1.f + __builtin_amdgcn_exp2f(-LOG2E * x)); }
;   DI void operator()(int tok0, int feat0, f32x16 (&acc)[2][2], int r, int hh) const {
;     const int u0 = (feat0 >> 6) * 32;
; #pragma unroll
;     for (int mt = 0; mt < 2; ++mt) {
;       bf16_t* dst = act + (size_t)(tok0 + mt * 32 + r) * DFF + u0 + 16 * hh;
; #pragma unroll
;       for (int gp = 0; gp < 2; ++gp) {
;         u32x4 o;
; #pragma unroll
;         for (int q = 0; q < 4; ++q) { const int i = 8 * gp + 2 * q; o[q] = pk2(siluf_(acc[0][mt][i]) * acc[1][mt][i], siluf_(acc[0][mt][i + 1]) * acc[1][mt][i + 1]); }
;         *(u32x4*)(dst + 8 * gp) = o;
;       }
;     }
;   }
; DI void grid_barrier(unsigned* ctr, const unsigned target) {
;   asm volatile("s_waitcnt vmcnt(0)" ::: "memory");
;   __syncthreads();
;   if (threadIdx.x == 0) {
;     __builtin_amdgcn_fence(__ATOMIC_RELEASE, "agent");
;     asm volatile("s_waitcnt vmcnt(0)" ::: "memory");
;     __hip_atomic_fetch_add((GAS unsigned*)ctr, 1u, __ATOMIC_RELAXED, __HIP_MEMORY_SCOPE_AGENT);
;     while (__hip_atomic_load((GAS unsigned*)ctr, __ATOMIC_RELAXED, __HIP_MEMORY_SCOPE_AGENT) < target) __builtin_amdgcn_s_sleep(1);
;     __builtin_amdgcn_fence(__ATOMIC_ACQUIRE, "agent");
;     asm volatile("s_waitcnt vmcnt(0)" ::: "memory");
;   }
;   __syncthreads();
; }
	s_nop 1
	v_pk_mul_f32 v[238:239], v[18:19], s[100:101] op_sel_hi:[1,0]
	v_pk_mul_f32 v[240:241], v[20:21], s[100:101] op_sel_hi:[1,0]
	v_pk_mul_f32 v[242:243], v[22:23], s[100:101] op_sel_hi:[1,0]
	v_pk_mul_f32 v[244:245], v[24:25], s[100:101] op_sel_hi:[1,0]
	v_exp_f32_e32 v238, v238
	v_exp_f32_e32 v239, v239
	v_exp_f32_e32 v240, v240
	v_exp_f32_e32 v241, v241
	v_exp_f32_e32 v242, v242
	v_exp_f32_e32 v243, v243
	v_exp_f32_e32 v244, v244
	v_exp_f32_e32 v245, v245
	v_pk_add_f32 v[238:239], v[238:239], 1.0 op_sel_hi:[1,0]
	v_pk_add_f32 v[240:241], v[240:241], 1.0 op_sel_hi:[1,0]
	v_pk_add_f32 v[242:243], v[242:243], 1.0 op_sel_hi:[1,0]
	v_pk_add_f32 v[244:245], v[244:245], 1.0 op_sel_hi:[1,0]
	v_rcp_f32_e32 v238, v238
	v_rcp_f32_e32 v239, v239
	v_rcp_f32_e32 v240, v240
	v_rcp_f32_e32 v241, v241
	v_rcp_f32_e32 v242, v242
	v_rcp_f32_e32 v243, v243
	v_rcp_f32_e32 v244, v244
	v_rcp_f32_e32 v245, v245
	v_pk_mul_f32 v[238:239], v[18:19], v[238:239]
	v_pk_mul_f32 v[240:241], v[20:21], v[240:241]
	v_pk_mul_f32 v[242:243], v[22:23], v[242:243]
	v_pk_mul_f32 v[244:245], v[24:25], v[244:245]
	v_pk_mul_f32 v[238:239], v[2:3], v[238:239]
	v_pk_mul_f32 v[240:241], v[4:5], v[240:241]
	v_pk_mul_f32 v[242:243], v[6:7], v[242:243]
	v_pk_mul_f32 v[244:245], v[8:9], v[244:245]
	v_cvt_pk_bf16_f32 v238, v238, v239
	v_cvt_pk_bf16_f32 v239, v240, v241
	v_cvt_pk_bf16_f32 v240, v242, v243
	v_cvt_pk_bf16_f32 v241, v244, v245
	global_store_dwordx4 v[188:189], v[238:241], off offset:64
	s_nop 1
	v_pk_mul_f32 v[238:239], v[26:27], s[100:101] op_sel_hi:[1,0]
	v_pk_mul_f32 v[240:241], v[28:29], s[100:101] op_sel_hi:[1,0]
	v_pk_mul_f32 v[242:243], v[30:31], s[100:101] op_sel_hi:[1,0]
	v_pk_mul_f32 v[244:245], v[32:33], s[100:101] op_sel_hi:[1,0]
	v_exp_f32_e32 v238, v238
	v_exp_f32_e32 v239, v239
	v_exp_f32_e32 v240, v240
	v_exp_f32_e32 v241, v241
	v_exp_f32_e32 v242, v242
	v_exp_f32_e32 v243, v243
	v_exp_f32_e32 v244, v244
	v_exp_f32_e32 v245, v245
	v_pk_add_f32 v[238:239], v[238:239], 1.0 op_sel_hi:[1,0]
	v_pk_add_f32 v[240:241], v[240:241], 1.0 op_sel_hi:[1,0]
	v_pk_add_f32 v[242:243], v[242:243], 1.0 op_sel_hi:[1,0]
	v_pk_add_f32 v[244:245], v[244:245], 1.0 op_sel_hi:[1,0]
	v_rcp_f32_e32 v238, v238
	v_rcp_f32_e32 v239, v239
	v_rcp_f32_e32 v240, v240
	v_rcp_f32_e32 v241, v241
	v_rcp_f32_e32 v242, v242
	v_rcp_f32_e32 v243, v243
	v_rcp_f32_e32 v244, v244
	v_rcp_f32_e32 v245, v245
	v_pk_mul_f32 v[238:239], v[26:27], v[238:239]
	v_pk_mul_f32 v[240:241], v[28:29], v[240:241]
	v_pk_mul_f32 v[242:243], v[30:31], v[242:243]
	v_pk_mul_f32 v[244:245], v[32:33], v[244:245]
	v_pk_mul_f32 v[238:239], v[10:11], v[238:239]
	v_pk_mul_f32 v[240:241], v[12:13], v[240:241]
	v_pk_mul_f32 v[242:243], v[14:15], v[242:243]
	v_pk_mul_f32 v[244:245], v[16:17], v[244:245]
	v_cvt_pk_bf16_f32 v238, v238, v239
	v_cvt_pk_bf16_f32 v239, v240, v241
	v_cvt_pk_bf16_f32 v240, v242, v243
	v_cvt_pk_bf16_f32 v241, v244, v245
	global_store_dwordx4 v[188:189], v[238:241], off offset:80
	s_nop 1
	s_and_b64 vcc, exec, s[4:5]
	s_mov_b32 s16, s9
	s_cbranch_vccz .LBB0_736
	s_add_i32 s25, s24, 1
	s_cmp_ge_i32 s25, s79
	s_cbranch_scc1 .LBB0_762
	s_cmp_lg_u32 s24, s78
	s_mov_b64 s[4:5], -1
	v_mov_b32_e32 v206, v198
	v_mov_b32_e32 v207, v199
	s_cbranch_scc0 .LBB0_750
	s_waitcnt vmcnt(0)
	s_barrier
	s_mov_b64 s[4:5], exec
	v_readlane_b32 s2, v254, 26
	v_readlane_b32 s3, v254, 27
	s_and_b64 s[2:3], s[4:5], s[2:3]
	s_mov_b64 exec, s[2:3]
	s_cbranch_execz .LBB0_749
	s_load_dword s2, s[80:81], 0x0
	s_mov_b64 s[8:9], exec
	buffer_wbl2 sc1
	s_waitcnt vmcnt(0) lgkmcnt(0)
	s_waitcnt vmcnt(0)
	v_mbcnt_lo_u32_b32 v0, s8, 0
	s_add_u32 s6, s10, 0x1ee14400
	v_mbcnt_hi_u32_b32 v0, s9, v0
	s_addc_u32 s7, s11, 0
	v_cmp_eq_u32_e32 vcc, 0, v0
	s_and_saveexec_b64 s[10:11], vcc
	s_cbranch_execz .LBB0_746
	s_bcnt1_i32_b64 s3, s[8:9]
	v_mov_b32_e32 v0, s3
	v_readlane_b32 s100, v254, 0
	s_and_b32 s100, s100, 7
	s_lshl_b32 s100, s100, 8
	s_add_u32 s100, s6, s100
	s_addc_u32 s101, s7, 0
	global_atomic_add v1, v0, s[100:101]
